# static wave priority in the gate_up / in_proj / down K-loops: no per-block setprio flips, waves 4-7 at priority 1 for the whole loop
# speedup vs baseline: 1.0140x; 1.0076x over previous
.LBB0_97:
	s_ashr_i32 s7, s6, 31
	s_lshl_b64 s[10:11], s[6:7], 19
	v_readlane_b32 s14, v255, 9
	v_readlane_b32 s15, v255, 10
	s_add_u32 s16, s14, s10
	s_addc_u32 s17, s15, s11
	s_and_b64 s[10:11], s[38:39], exec
	s_cselect_b32 s7, s17, s45
	s_cselect_b32 s10, s16, s44
	s_ashr_i32 s5, s4, 31
	s_lshl_b64 s[14:15], s[4:5], 19
	s_add_u32 s40, s26, s14
	s_addc_u32 s41, s27, s15
	s_and_b64 s[14:15], s[38:39], exec
	s_cselect_b32 s5, s41, s47
	s_cselect_b32 s11, s40, s46
	s_add_u32 s44, s44, 0x40080
	s_addc_u32 s45, s45, 0
	s_add_u32 s13, s46, 0x100
	v_mov_b32_e32 v4, 0
	s_addc_u32 s14, s47, 0
	s_mov_b32 s15, -2
	v_mov_b32_e32 v5, v4
	v_mov_b32_e32 v6, v4
	v_mov_b32_e32 v7, v4
	v_mov_b32_e32 v12, v4
	v_mov_b32_e32 v13, v4
	v_mov_b32_e32 v14, v4
	v_mov_b32_e32 v15, v4
	v_mov_b32_e32 v20, v4
	v_mov_b32_e32 v21, v4
	v_mov_b32_e32 v22, v4
	v_mov_b32_e32 v23, v4
	v_mov_b32_e32 v28, v4
	v_mov_b32_e32 v29, v4
	v_mov_b32_e32 v30, v4
	v_mov_b32_e32 v31, v4
	v_mov_b32_e32 v36, v4
	v_mov_b32_e32 v37, v4
	v_mov_b32_e32 v38, v4
	v_mov_b32_e32 v39, v4
	v_mov_b32_e32 v44, v4
	v_mov_b32_e32 v45, v4
	v_mov_b32_e32 v46, v4
	v_mov_b32_e32 v47, v4
	v_mov_b32_e32 v52, v4
	v_mov_b32_e32 v53, v4
	v_mov_b32_e32 v54, v4
	v_mov_b32_e32 v55, v4
	v_mov_b32_e32 v60, v4
	v_mov_b32_e32 v61, v4
	v_mov_b32_e32 v62, v4
	v_mov_b32_e32 v63, v4
	v_mov_b32_e32 v8, v4
	v_mov_b32_e32 v9, v4
	v_mov_b32_e32 v10, v4
	v_mov_b32_e32 v11, v4
	v_mov_b32_e32 v16, v4
	v_mov_b32_e32 v17, v4
	v_mov_b32_e32 v18, v4
	v_mov_b32_e32 v19, v4
	v_mov_b32_e32 v24, v4
	v_mov_b32_e32 v25, v4
	v_mov_b32_e32 v26, v4
	v_mov_b32_e32 v27, v4
	v_mov_b32_e32 v32, v4
	v_mov_b32_e32 v33, v4
	v_mov_b32_e32 v34, v4
	v_mov_b32_e32 v35, v4
	v_mov_b32_e32 v40, v4
	v_mov_b32_e32 v41, v4
	v_mov_b32_e32 v42, v4
	v_mov_b32_e32 v43, v4
	v_mov_b32_e32 v48, v4
	v_mov_b32_e32 v49, v4
	v_mov_b32_e32 v50, v4
	v_mov_b32_e32 v51, v4
	v_mov_b32_e32 v56, v4
	v_mov_b32_e32 v57, v4
	v_mov_b32_e32 v58, v4
	v_mov_b32_e32 v59, v4
	v_mov_b32_e32 v64, v4
	v_mov_b32_e32 v65, v4
	v_mov_b32_e32 v66, v4
	v_mov_b32_e32 v67, v4
	v_mov_b32_e32 v68, v4
	v_mov_b32_e32 v69, v4
	v_mov_b32_e32 v70, v4
	v_mov_b32_e32 v71, v4
	v_mov_b32_e32 v76, v4
	v_mov_b32_e32 v77, v4
	v_mov_b32_e32 v78, v4
	v_mov_b32_e32 v79, v4
	v_mov_b32_e32 v84, v4
	v_mov_b32_e32 v85, v4
	v_mov_b32_e32 v86, v4
	v_mov_b32_e32 v87, v4
	v_mov_b32_e32 v92, v4
	v_mov_b32_e32 v93, v4
	v_mov_b32_e32 v94, v4
	v_mov_b32_e32 v95, v4
	v_mov_b32_e32 v100, v4
	v_mov_b32_e32 v101, v4
	v_mov_b32_e32 v102, v4
	v_mov_b32_e32 v103, v4
	v_mov_b32_e32 v108, v4
	v_mov_b32_e32 v109, v4
	v_mov_b32_e32 v110, v4
	v_mov_b32_e32 v111, v4
	v_mov_b32_e32 v116, v4
	v_mov_b32_e32 v117, v4
	v_mov_b32_e32 v118, v4
	v_mov_b32_e32 v119, v4
	v_mov_b32_e32 v124, v4
	v_mov_b32_e32 v125, v4
	v_mov_b32_e32 v126, v4
	v_mov_b32_e32 v127, v4
	v_mov_b32_e32 v72, v4
	v_mov_b32_e32 v73, v4
	v_mov_b32_e32 v74, v4
	v_mov_b32_e32 v75, v4
	v_mov_b32_e32 v80, v4
	v_mov_b32_e32 v81, v4
	v_mov_b32_e32 v82, v4
	v_mov_b32_e32 v83, v4
	v_mov_b32_e32 v88, v4
	v_mov_b32_e32 v89, v4
	v_mov_b32_e32 v90, v4
	v_mov_b32_e32 v91, v4
	v_mov_b32_e32 v96, v4
	v_mov_b32_e32 v97, v4
	v_mov_b32_e32 v98, v4
	v_mov_b32_e32 v99, v4
	v_mov_b32_e32 v104, v4
	v_mov_b32_e32 v105, v4
	v_mov_b32_e32 v106, v4
	v_mov_b32_e32 v107, v4
	v_mov_b32_e32 v112, v4
	v_mov_b32_e32 v113, v4
	v_mov_b32_e32 v114, v4
	v_mov_b32_e32 v115, v4
	v_mov_b32_e32 v120, v4
	v_mov_b32_e32 v121, v4
	v_mov_b32_e32 v122, v4
	v_mov_b32_e32 v123, v4
	v_mov_b32_e32 v128, v4
	v_mov_b32_e32 v129, v4
	v_mov_b32_e32 v130, v4
	v_mov_b32_e32 v131, v4
	v_readfirstlane_b32 s100, v207
	s_bitcmp1_b32 s100, 8
	s_cbranch_scc0 .Lprio_skip_98
	s_setprio 1
.Lprio_skip_98:
.LBB0_98:
	s_add_u32 s18, s44, 0xfffc0080
	s_addc_u32 s19, s45, -1
	s_add_i32 s46, 0, 0x10000
	s_cmp_eq_u32 s15, 12
	s_cselect_b32 s25, s7, s19
	s_cselect_b32 s24, s10, s18
	v_add_u32_e32 v148, s46, v150
	s_cselect_b32 s23, s5, s14
	s_cselect_b32 s22, s11, s13
	s_add_i32 s47, 0, 0x14000
	ds_read_b128 v[156:159], v148
	ds_read_b128 v[160:163], v148 offset:1024
	ds_read_b128 v[164:167], v148 offset:2048
	ds_read_b128 v[168:171], v148 offset:3072
	v_add_u32_e32 v148, s47, v150
	ds_read_b128 v[172:175], v148
	ds_read_b128 v[176:179], v148 offset:1024
	ds_read_b128 v[180:183], v148 offset:2048
	ds_read_b128 v[184:187], v148 offset:3072
	v_lshl_add_u64 v[148:149], s[44:45], 0, v[144:145]
	s_add_i32 m0, s29, 0xc000
	ds_read_b128 v[208:211], v155
	ds_read_b128 v[212:215], v155 offset:1024
	ds_read_b128 v[216:219], v155 offset:2048
	ds_read_b128 v[220:223], v155 offset:3072
	ds_read_b128 v[224:227], v155 offset:4096
	ds_read_b128 v[228:231], v155 offset:5120
	ds_read_b128 v[232:235], v155 offset:6144
	ds_read_b128 v[236:239], v155 offset:7168
	global_load_lds_dwordx4 v[148:149], off
	v_lshl_add_u64 v[148:149], s[44:45], 0, v[146:147]
	s_add_i32 m0, s29, 0xe000
	s_nop 0
	global_load_lds_dwordx4 v[148:149], off
	s_waitcnt vmcnt(8)
	s_waitcnt lgkmcnt(0)
	s_barrier
	s_waitcnt lgkmcnt(0)
	v_mfma_f32_16x16x32_bf16 v[128:131], v[156:159], v[208:211], v[128:131]
	v_mfma_f32_16x16x32_bf16 v[120:123], v[164:167], v[208:211], v[120:123]
	v_mfma_f32_16x16x32_bf16 v[112:115], v[156:159], v[216:219], v[112:115]
	v_mfma_f32_16x16x32_bf16 v[104:107], v[164:167], v[216:219], v[104:107]
	v_mfma_f32_16x16x32_bf16 v[96:99], v[156:159], v[224:227], v[96:99]
	v_mfma_f32_16x16x32_bf16 v[88:91], v[164:167], v[224:227], v[88:91]
	v_mfma_f32_16x16x32_bf16 v[80:83], v[156:159], v[232:235], v[80:83]
	v_mfma_f32_16x16x32_bf16 v[72:75], v[164:167], v[232:235], v[72:75]
	v_mfma_f32_16x16x32_bf16 v[128:131], v[160:163], v[212:215], v[128:131]
	v_mfma_f32_16x16x32_bf16 v[120:123], v[168:171], v[212:215], v[120:123]
	v_mfma_f32_16x16x32_bf16 v[112:115], v[160:163], v[220:223], v[112:115]
	v_mfma_f32_16x16x32_bf16 v[104:107], v[168:171], v[220:223], v[104:107]
	v_mfma_f32_16x16x32_bf16 v[96:99], v[160:163], v[228:231], v[96:99]
	v_mfma_f32_16x16x32_bf16 v[88:91], v[168:171], v[228:231], v[88:91]
	v_mfma_f32_16x16x32_bf16 v[80:83], v[160:163], v[236:239], v[80:83]
	v_mfma_f32_16x16x32_bf16 v[72:75], v[168:171], v[236:239], v[72:75]
	v_mfma_f32_16x16x32_bf16 v[124:127], v[172:175], v[208:211], v[124:127]
	v_mfma_f32_16x16x32_bf16 v[116:119], v[180:183], v[208:211], v[116:119]
	v_mfma_f32_16x16x32_bf16 v[108:111], v[172:175], v[216:219], v[108:111]
	v_mfma_f32_16x16x32_bf16 v[100:103], v[180:183], v[216:219], v[100:103]
	v_mfma_f32_16x16x32_bf16 v[92:95], v[172:175], v[224:227], v[92:95]
	v_mfma_f32_16x16x32_bf16 v[84:87], v[180:183], v[224:227], v[84:87]
	v_mfma_f32_16x16x32_bf16 v[76:79], v[172:175], v[232:235], v[76:79]
	v_mfma_f32_16x16x32_bf16 v[68:71], v[180:183], v[232:235], v[68:71]
	v_mfma_f32_16x16x32_bf16 v[124:127], v[176:179], v[212:215], v[124:127]
	v_mfma_f32_16x16x32_bf16 v[116:119], v[184:187], v[212:215], v[116:119]
	v_mfma_f32_16x16x32_bf16 v[108:111], v[176:179], v[220:223], v[108:111]
	v_mfma_f32_16x16x32_bf16 v[100:103], v[184:187], v[220:223], v[100:103]
	v_mfma_f32_16x16x32_bf16 v[92:95], v[176:179], v[228:231], v[92:95]
	v_mfma_f32_16x16x32_bf16 v[84:87], v[184:187], v[228:231], v[84:87]
	v_mfma_f32_16x16x32_bf16 v[76:79], v[176:179], v[236:239], v[76:79]
	v_mfma_f32_16x16x32_bf16 v[68:71], v[184:187], v[236:239], v[68:71]
	s_barrier
	s_add_i32 s18, s46, s28
	v_lshl_add_u64 v[148:149], s[22:23], 0, v[2:3]
	s_mov_b32 m0, s18
	ds_read_b128 v[208:211], v155 offset:16384
	ds_read_b128 v[212:215], v155 offset:17408
	ds_read_b128 v[216:219], v155 offset:18432
	ds_read_b128 v[220:223], v155 offset:19456
	ds_read_b128 v[224:227], v155 offset:20480
	ds_read_b128 v[228:231], v155 offset:21504
	ds_read_b128 v[232:235], v155 offset:22528
	ds_read_b128 v[236:239], v155 offset:23552
	global_load_lds_dwordx4 v[148:149], off
	s_add_i32 m0, s18, 0x2000
	s_add_u32 s18, s22, 0x40000
	v_lshl_add_u64 v[188:189], s[22:23], 0, v[142:143]
	s_addc_u32 s19, s23, 0
	s_add_i32 s46, s47, s28
	global_load_lds_dwordx4 v[188:189], off
	v_lshl_add_u64 v[196:197], s[18:19], 0, v[2:3]
	s_mov_b32 m0, s46
	v_lshl_add_u64 v[198:199], s[24:25], 0, v[140:141]
	global_load_lds_dwordx4 v[196:197], off
	v_lshl_add_u64 v[196:197], s[18:19], 0, v[142:143]
	s_add_i32 m0, s46, 0x2000
	s_nop 0
	global_load_lds_dwordx4 v[196:197], off
	v_lshl_add_u64 v[196:197], s[24:25], 0, v[0:1]
	s_mov_b32 m0, s29
	s_nop 0
	global_load_lds_dwordx4 v[196:197], off
	s_mov_b32 m0, s43
	s_nop 0
	global_load_lds_dwordx4 v[198:199], off
	s_waitcnt vmcnt(8)
	s_waitcnt lgkmcnt(0)
	s_barrier
	s_waitcnt lgkmcnt(0)
	v_mfma_f32_16x16x32_bf16 v[64:67], v[156:159], v[208:211], v[64:67]
	v_mfma_f32_16x16x32_bf16 v[56:59], v[164:167], v[208:211], v[56:59]
	v_mfma_f32_16x16x32_bf16 v[48:51], v[156:159], v[216:219], v[48:51]
	v_mfma_f32_16x16x32_bf16 v[40:43], v[164:167], v[216:219], v[40:43]
	v_mfma_f32_16x16x32_bf16 v[32:35], v[156:159], v[224:227], v[32:35]
	v_mfma_f32_16x16x32_bf16 v[24:27], v[164:167], v[224:227], v[24:27]
	v_mfma_f32_16x16x32_bf16 v[16:19], v[156:159], v[232:235], v[16:19]
	v_mfma_f32_16x16x32_bf16 v[8:11], v[164:167], v[232:235], v[8:11]
	v_mfma_f32_16x16x32_bf16 v[64:67], v[160:163], v[212:215], v[64:67]
	v_mfma_f32_16x16x32_bf16 v[56:59], v[168:171], v[212:215], v[56:59]
	v_mfma_f32_16x16x32_bf16 v[48:51], v[160:163], v[220:223], v[48:51]
	v_mfma_f32_16x16x32_bf16 v[40:43], v[168:171], v[220:223], v[40:43]
	v_mfma_f32_16x16x32_bf16 v[32:35], v[160:163], v[228:231], v[32:35]
	v_mfma_f32_16x16x32_bf16 v[24:27], v[168:171], v[228:231], v[24:27]
	v_mfma_f32_16x16x32_bf16 v[16:19], v[160:163], v[236:239], v[16:19]
	v_mfma_f32_16x16x32_bf16 v[8:11], v[168:171], v[236:239], v[8:11]
	v_mfma_f32_16x16x32_bf16 v[60:63], v[172:175], v[208:211], v[60:63]
	v_mfma_f32_16x16x32_bf16 v[52:55], v[180:183], v[208:211], v[52:55]
	v_mfma_f32_16x16x32_bf16 v[44:47], v[172:175], v[216:219], v[44:47]
	v_mfma_f32_16x16x32_bf16 v[36:39], v[180:183], v[216:219], v[36:39]
	v_mfma_f32_16x16x32_bf16 v[28:31], v[172:175], v[224:227], v[28:31]
	v_mfma_f32_16x16x32_bf16 v[20:23], v[180:183], v[224:227], v[20:23]
	v_mfma_f32_16x16x32_bf16 v[12:15], v[172:175], v[232:235], v[12:15]
	v_mfma_f32_16x16x32_bf16 v[4:7], v[180:183], v[232:235], v[4:7]
	v_mfma_f32_16x16x32_bf16 v[60:63], v[176:179], v[212:215], v[60:63]
	v_mfma_f32_16x16x32_bf16 v[52:55], v[184:187], v[212:215], v[52:55]
	v_mfma_f32_16x16x32_bf16 v[44:47], v[176:179], v[220:223], v[44:47]
	v_mfma_f32_16x16x32_bf16 v[36:39], v[184:187], v[220:223], v[36:39]
	v_mfma_f32_16x16x32_bf16 v[28:31], v[176:179], v[228:231], v[28:31]
	v_mfma_f32_16x16x32_bf16 v[20:23], v[184:187], v[228:231], v[20:23]
	v_mfma_f32_16x16x32_bf16 v[12:15], v[176:179], v[236:239], v[12:15]
	v_mfma_f32_16x16x32_bf16 v[4:7], v[184:187], v[236:239], v[4:7]
	s_barrier
	s_add_i32 s46, 0, 0x18000
	s_add_i32 s47, 0, 0x1c000
	v_add_u32_e32 v168, s46, v150
	v_add_u32_e32 v184, s47, v150
	ds_read_b128 v[156:159], v168
	ds_read_b128 v[160:163], v168 offset:1024
	ds_read_b128 v[164:167], v168 offset:2048
	ds_read_b128 v[168:171], v168 offset:3072
	ds_read_b128 v[172:175], v184
	ds_read_b128 v[176:179], v184 offset:1024
	ds_read_b128 v[180:183], v184 offset:2048
	ds_read_b128 v[184:187], v184 offset:3072
	s_add_u32 s18, s24, 0x40000
	s_addc_u32 s19, s25, 0
	s_mov_b32 m0, s48
	v_lshl_add_u64 v[200:201], s[18:19], 0, v[0:1]
	ds_read_b128 v[208:211], v155 offset:32768
	ds_read_b128 v[212:215], v155 offset:33792
	ds_read_b128 v[216:219], v155 offset:34816
	ds_read_b128 v[220:223], v155 offset:35840
	ds_read_b128 v[224:227], v155 offset:36864
	ds_read_b128 v[228:231], v155 offset:37888
	ds_read_b128 v[232:235], v155 offset:38912
	ds_read_b128 v[236:239], v155 offset:39936
	global_load_lds_dwordx4 v[200:201], off
	v_lshl_add_u64 v[200:201], s[18:19], 0, v[140:141]
	s_mov_b32 m0, s49
	s_nop 0
	global_load_lds_dwordx4 v[200:201], off
	s_waitcnt vmcnt(8)
	s_waitcnt lgkmcnt(0)
	s_barrier
	s_waitcnt lgkmcnt(0)
	v_mfma_f32_16x16x32_bf16 v[128:131], v[156:159], v[208:211], v[128:131]
	v_mfma_f32_16x16x32_bf16 v[120:123], v[164:167], v[208:211], v[120:123]
	v_mfma_f32_16x16x32_bf16 v[112:115], v[156:159], v[216:219], v[112:115]
	v_mfma_f32_16x16x32_bf16 v[104:107], v[164:167], v[216:219], v[104:107]
	v_mfma_f32_16x16x32_bf16 v[96:99], v[156:159], v[224:227], v[96:99]
	v_mfma_f32_16x16x32_bf16 v[88:91], v[164:167], v[224:227], v[88:91]
	v_mfma_f32_16x16x32_bf16 v[80:83], v[156:159], v[232:235], v[80:83]
	v_mfma_f32_16x16x32_bf16 v[72:75], v[164:167], v[232:235], v[72:75]
	v_mfma_f32_16x16x32_bf16 v[128:131], v[160:163], v[212:215], v[128:131]
	v_mfma_f32_16x16x32_bf16 v[120:123], v[168:171], v[212:215], v[120:123]
	v_mfma_f32_16x16x32_bf16 v[112:115], v[160:163], v[220:223], v[112:115]
	v_mfma_f32_16x16x32_bf16 v[104:107], v[168:171], v[220:223], v[104:107]
	v_mfma_f32_16x16x32_bf16 v[96:99], v[160:163], v[228:231], v[96:99]
	v_mfma_f32_16x16x32_bf16 v[88:91], v[168:171], v[228:231], v[88:91]
	v_mfma_f32_16x16x32_bf16 v[80:83], v[160:163], v[236:239], v[80:83]
	v_mfma_f32_16x16x32_bf16 v[72:75], v[168:171], v[236:239], v[72:75]
	v_mfma_f32_16x16x32_bf16 v[124:127], v[172:175], v[208:211], v[124:127]
	v_mfma_f32_16x16x32_bf16 v[116:119], v[180:183], v[208:211], v[116:119]
	v_mfma_f32_16x16x32_bf16 v[108:111], v[172:175], v[216:219], v[108:111]
	v_mfma_f32_16x16x32_bf16 v[100:103], v[180:183], v[216:219], v[100:103]
	v_mfma_f32_16x16x32_bf16 v[92:95], v[172:175], v[224:227], v[92:95]
	v_mfma_f32_16x16x32_bf16 v[84:87], v[180:183], v[224:227], v[84:87]
	v_mfma_f32_16x16x32_bf16 v[76:79], v[172:175], v[232:235], v[76:79]
	v_mfma_f32_16x16x32_bf16 v[68:71], v[180:183], v[232:235], v[68:71]
	v_mfma_f32_16x16x32_bf16 v[124:127], v[176:179], v[212:215], v[124:127]
	v_mfma_f32_16x16x32_bf16 v[116:119], v[184:187], v[212:215], v[116:119]
	v_mfma_f32_16x16x32_bf16 v[108:111], v[176:179], v[220:223], v[108:111]
	v_mfma_f32_16x16x32_bf16 v[100:103], v[184:187], v[220:223], v[100:103]
	v_mfma_f32_16x16x32_bf16 v[92:95], v[176:179], v[228:231], v[92:95]
	v_mfma_f32_16x16x32_bf16 v[84:87], v[184:187], v[228:231], v[84:87]
	v_mfma_f32_16x16x32_bf16 v[76:79], v[176:179], v[236:239], v[76:79]
	v_mfma_f32_16x16x32_bf16 v[68:71], v[184:187], v[236:239], v[68:71]
	s_barrier
	s_add_i32 s18, s46, s28
	v_lshl_add_u64 v[148:149], v[148:149], 0, s[92:93]
	s_mov_b32 m0, s18
	ds_read_b128 v[208:211], v155 offset:49152
	ds_read_b128 v[212:215], v155 offset:50176
	ds_read_b128 v[216:219], v155 offset:51200
	ds_read_b128 v[220:223], v155 offset:52224
	ds_read_b128 v[224:227], v155 offset:53248
	ds_read_b128 v[228:231], v155 offset:54272
	ds_read_b128 v[232:235], v155 offset:55296
	ds_read_b128 v[236:239], v155 offset:56320
	global_load_lds_dwordx4 v[148:149], off
	s_add_i32 m0, s18, 0x2000
	s_add_u32 s18, s22, 0x40080
	v_lshl_add_u64 v[148:149], v[188:189], 0, s[92:93]
	s_addc_u32 s19, s23, 0
	s_add_i32 s22, s47, s28
	global_load_lds_dwordx4 v[148:149], off
	v_lshl_add_u64 v[148:149], s[18:19], 0, v[2:3]
	s_mov_b32 m0, s22
	s_nop 0
	global_load_lds_dwordx4 v[148:149], off
	v_lshl_add_u64 v[148:149], s[18:19], 0, v[142:143]
	s_add_i32 m0, s22, 0x2000
	s_nop 0
	global_load_lds_dwordx4 v[148:149], off
	v_lshl_add_u64 v[148:149], v[196:197], 0, s[92:93]
	s_mov_b32 m0, s50
	s_nop 0
	global_load_lds_dwordx4 v[148:149], off
	v_lshl_add_u64 v[148:149], v[198:199], 0, s[92:93]
	s_mov_b32 m0, s51
	s_nop 0
	global_load_lds_dwordx4 v[148:149], off
	s_waitcnt vmcnt(8)
	s_waitcnt lgkmcnt(0)
	s_barrier
	s_waitcnt lgkmcnt(0)
	v_mfma_f32_16x16x32_bf16 v[64:67], v[156:159], v[208:211], v[64:67]
	v_mfma_f32_16x16x32_bf16 v[56:59], v[164:167], v[208:211], v[56:59]
	v_mfma_f32_16x16x32_bf16 v[48:51], v[156:159], v[216:219], v[48:51]
	v_mfma_f32_16x16x32_bf16 v[40:43], v[164:167], v[216:219], v[40:43]
	v_mfma_f32_16x16x32_bf16 v[32:35], v[156:159], v[224:227], v[32:35]
	v_mfma_f32_16x16x32_bf16 v[24:27], v[164:167], v[224:227], v[24:27]
	v_mfma_f32_16x16x32_bf16 v[16:19], v[156:159], v[232:235], v[16:19]
	v_mfma_f32_16x16x32_bf16 v[8:11], v[164:167], v[232:235], v[8:11]
	v_mfma_f32_16x16x32_bf16 v[64:67], v[160:163], v[212:215], v[64:67]
	v_mfma_f32_16x16x32_bf16 v[56:59], v[168:171], v[212:215], v[56:59]
	v_mfma_f32_16x16x32_bf16 v[48:51], v[160:163], v[220:223], v[48:51]
	v_mfma_f32_16x16x32_bf16 v[40:43], v[168:171], v[220:223], v[40:43]
	v_mfma_f32_16x16x32_bf16 v[32:35], v[160:163], v[228:231], v[32:35]
	v_mfma_f32_16x16x32_bf16 v[24:27], v[168:171], v[228:231], v[24:27]
	v_mfma_f32_16x16x32_bf16 v[16:19], v[160:163], v[236:239], v[16:19]
	v_mfma_f32_16x16x32_bf16 v[8:11], v[168:171], v[236:239], v[8:11]
	v_mfma_f32_16x16x32_bf16 v[60:63], v[172:175], v[208:211], v[60:63]
	v_mfma_f32_16x16x32_bf16 v[52:55], v[180:183], v[208:211], v[52:55]
	v_mfma_f32_16x16x32_bf16 v[44:47], v[172:175], v[216:219], v[44:47]
	v_mfma_f32_16x16x32_bf16 v[36:39], v[180:183], v[216:219], v[36:39]
	v_mfma_f32_16x16x32_bf16 v[28:31], v[172:175], v[224:227], v[28:31]
	v_mfma_f32_16x16x32_bf16 v[20:23], v[180:183], v[224:227], v[20:23]
	v_mfma_f32_16x16x32_bf16 v[12:15], v[172:175], v[232:235], v[12:15]
	v_mfma_f32_16x16x32_bf16 v[4:7], v[180:183], v[232:235], v[4:7]
	v_mfma_f32_16x16x32_bf16 v[60:63], v[176:179], v[212:215], v[60:63]
	v_mfma_f32_16x16x32_bf16 v[52:55], v[184:187], v[212:215], v[52:55]
	v_mfma_f32_16x16x32_bf16 v[44:47], v[176:179], v[220:223], v[44:47]
	v_mfma_f32_16x16x32_bf16 v[36:39], v[184:187], v[220:223], v[36:39]
	v_mfma_f32_16x16x32_bf16 v[28:31], v[176:179], v[228:231], v[28:31]
	v_mfma_f32_16x16x32_bf16 v[20:23], v[184:187], v[228:231], v[20:23]
	v_mfma_f32_16x16x32_bf16 v[12:15], v[176:179], v[236:239], v[12:15]
	v_mfma_f32_16x16x32_bf16 v[4:7], v[184:187], v[236:239], v[4:7]
	s_barrier
	s_add_i32 s15, s15, 2
	s_add_u32 s44, s44, 0x100
	s_addc_u32 s45, s45, 0
	s_add_u32 s13, s13, 0x100
	s_addc_u32 s14, s14, 0
	s_cmp_gt_u32 s15, 13
	s_cbranch_scc0 .LBB0_98
	s_setprio 0
	s_lshl_b32 s5, s42, 8
	s_and_b64 vcc, exec, s[2:3]
	s_cbranch_vccz .LBB0_101
	v_or_b32_e32 v148, s5, v152
	v_ashrrev_i32_e32 v149, 31, v148
	v_readlane_b32 s10, v255, 11
	v_lshlrev_b64 v[148:149], 6, v[148:149]
	v_readlane_b32 s11, v255, 12
	s_nop 1
	v_lshl_add_u64 v[148:149], s[10:11], 0, v[148:149]
	global_load_dwordx4 v[156:159], v[148:149], off
	global_load_dwordx4 v[160:163], v[148:149], off offset:32
	global_load_dwordx4 v[164:167], v[148:149], off offset:16
	global_load_dwordx4 v[168:171], v[148:149], off offset:48
	s_barrier

.LBB0_810:
	s_add_u32 s13, s24, 0x100
	v_mov_b32_e32 v4, 0
	s_addc_u32 s14, s25, 0
	s_mov_b32 s15, -2
	v_mov_b32_e32 v5, v4
	v_mov_b32_e32 v6, v4
	v_mov_b32_e32 v7, v4
	v_mov_b32_e32 v8, v4
	s_waitcnt lgkmcnt(0)
	v_mov_b32_e32 v9, v4
	v_mov_b32_e32 v10, v4
	v_mov_b32_e32 v11, v4
	v_mov_b32_e32 v20, v4
	v_mov_b32_e32 v21, v4
	v_mov_b32_e32 v22, v4
	v_mov_b32_e32 v23, v4
	v_mov_b32_e32 v24, v4
	v_mov_b32_e32 v25, v4
	v_mov_b32_e32 v26, v4
	v_mov_b32_e32 v27, v4
	v_mov_b32_e32 v36, v4
	v_mov_b32_e32 v37, v4
	v_mov_b32_e32 v38, v4
	v_mov_b32_e32 v39, v4
	v_mov_b32_e32 v40, v4
	v_mov_b32_e32 v41, v4
	v_mov_b32_e32 v42, v4
	v_mov_b32_e32 v43, v4
	v_mov_b32_e32 v52, v4
	v_mov_b32_e32 v53, v4
	v_mov_b32_e32 v54, v4
	v_mov_b32_e32 v55, v4
	v_mov_b32_e32 v56, v4
	v_mov_b32_e32 v57, v4
	v_mov_b32_e32 v58, v4
	v_mov_b32_e32 v59, v4
	v_mov_b32_e32 v12, v4
	v_mov_b32_e32 v13, v4
	v_mov_b32_e32 v14, v4
	v_mov_b32_e32 v15, v4
	v_mov_b32_e32 v16, v4
	v_mov_b32_e32 v17, v4
	v_mov_b32_e32 v18, v4
	v_mov_b32_e32 v19, v4
	v_mov_b32_e32 v28, v4
	v_mov_b32_e32 v29, v4
	v_mov_b32_e32 v30, v4
	v_mov_b32_e32 v31, v4
	v_mov_b32_e32 v32, v4
	v_mov_b32_e32 v33, v4
	v_mov_b32_e32 v34, v4
	v_mov_b32_e32 v35, v4
	v_mov_b32_e32 v44, v4
	v_mov_b32_e32 v45, v4
	v_mov_b32_e32 v46, v4
	v_mov_b32_e32 v47, v4
	v_mov_b32_e32 v48, v4
	v_mov_b32_e32 v49, v4
	v_mov_b32_e32 v50, v4
	v_mov_b32_e32 v51, v4
	v_mov_b32_e32 v60, v4
	v_mov_b32_e32 v61, v4
	v_mov_b32_e32 v62, v4
	v_mov_b32_e32 v63, v4
	v_mov_b32_e32 v64, v4
	v_mov_b32_e32 v65, v4
	v_mov_b32_e32 v66, v4
	v_mov_b32_e32 v67, v4
	v_mov_b32_e32 v68, v4
	v_mov_b32_e32 v69, v4
	v_mov_b32_e32 v70, v4
	v_mov_b32_e32 v71, v4
	v_mov_b32_e32 v72, v4
	v_mov_b32_e32 v73, v4
	v_mov_b32_e32 v74, v4
	v_mov_b32_e32 v75, v4
	v_mov_b32_e32 v84, v4
	v_mov_b32_e32 v85, v4
	v_mov_b32_e32 v86, v4
	v_mov_b32_e32 v87, v4
	v_mov_b32_e32 v88, v4
	v_mov_b32_e32 v89, v4
	v_mov_b32_e32 v90, v4
	v_mov_b32_e32 v91, v4
	v_mov_b32_e32 v100, v4
	v_mov_b32_e32 v101, v4
	v_mov_b32_e32 v102, v4
	v_mov_b32_e32 v103, v4
	v_mov_b32_e32 v104, v4
	v_mov_b32_e32 v105, v4
	v_mov_b32_e32 v106, v4
	v_mov_b32_e32 v107, v4
	v_mov_b32_e32 v116, v4
	v_mov_b32_e32 v117, v4
	v_mov_b32_e32 v118, v4
	v_mov_b32_e32 v119, v4
	v_mov_b32_e32 v120, v4
	v_mov_b32_e32 v121, v4
	v_mov_b32_e32 v122, v4
	v_mov_b32_e32 v123, v4
	v_mov_b32_e32 v76, v4
	v_mov_b32_e32 v77, v4
	v_mov_b32_e32 v78, v4
	v_mov_b32_e32 v79, v4
	v_mov_b32_e32 v80, v4
	v_mov_b32_e32 v81, v4
	v_mov_b32_e32 v82, v4
	v_mov_b32_e32 v83, v4
	v_mov_b32_e32 v92, v4
	v_mov_b32_e32 v93, v4
	v_mov_b32_e32 v94, v4
	v_mov_b32_e32 v95, v4
	v_mov_b32_e32 v96, v4
	v_mov_b32_e32 v97, v4
	v_mov_b32_e32 v98, v4
	v_mov_b32_e32 v99, v4
	v_mov_b32_e32 v108, v4
	v_mov_b32_e32 v109, v4
	v_mov_b32_e32 v110, v4
	v_mov_b32_e32 v111, v4
	v_mov_b32_e32 v112, v4
	v_mov_b32_e32 v113, v4
	v_mov_b32_e32 v114, v4
	v_mov_b32_e32 v115, v4
	v_mov_b32_e32 v124, v4
	v_mov_b32_e32 v125, v4
	v_mov_b32_e32 v126, v4
	v_mov_b32_e32 v127, v4
	v_mov_b32_e32 v128, v4
	v_mov_b32_e32 v129, v4
	v_mov_b32_e32 v130, v4
	v_mov_b32_e32 v131, v4
	v_readfirstlane_b32 s100, v207
	s_bitcmp1_b32 s100, 8
	s_cbranch_scc0 .Lprio_skip_811
	s_setprio 1
.Lprio_skip_811:
.LBB0_811:
	s_add_u32 s42, s44, 0x100
	s_addc_u32 s43, s45, 0
	s_add_i32 s18, 0, 0x10000
	s_cmp_eq_u32 s15, 40
	s_cselect_b32 s25, s11, s43
	s_cselect_b32 s24, s10, s42
	s_cselect_b32 s23, s17, s14
	s_cselect_b32 s22, s16, s13
	s_add_i32 s62, 0, 0x14000
	v_add_u32_e32 v156, s18, v210
	v_add_u32_e32 v172, s62, v210
	ds_read_b128 v[144:147], v156
	ds_read_b128 v[148:151], v156 offset:1024
	ds_read_b128 v[152:155], v156 offset:2048
	ds_read_b128 v[156:159], v156 offset:3072
	ds_read_b128 v[160:163], v172
	ds_read_b128 v[164:167], v172 offset:1024
	ds_read_b128 v[168:171], v172 offset:2048
	ds_read_b128 v[172:175], v172 offset:3072
	v_lshl_add_u64 v[188:189], s[44:45], 0, v[140:141]
	s_add_i32 m0, s47, 0xc000
	ds_read_b128 v[176:179], v212
	ds_read_b128 v[180:183], v212 offset:1024
	ds_read_b128 v[184:187], v212 offset:2048
	ds_read_b128 v[214:217], v212 offset:3072
	ds_read_b128 v[218:221], v212 offset:4096
	ds_read_b128 v[222:225], v212 offset:5120
	ds_read_b128 v[226:229], v212 offset:6144
	ds_read_b128 v[230:233], v212 offset:7168
	global_load_lds_dwordx4 v[188:189], off
	v_lshl_add_u64 v[188:189], s[44:45], 0, v[142:143]
	s_add_i32 m0, s47, 0xe000
	s_nop 0
	global_load_lds_dwordx4 v[188:189], off
	s_waitcnt vmcnt(8)
	s_waitcnt lgkmcnt(0)
	s_barrier
	s_waitcnt lgkmcnt(0)
	v_mfma_f32_16x16x32_bf16 v[128:131], v[144:147], v[176:179], v[128:131]
	v_mfma_f32_16x16x32_bf16 v[124:127], v[152:155], v[176:179], v[124:127]
	v_mfma_f32_16x16x32_bf16 v[112:115], v[144:147], v[184:187], v[112:115]
	v_mfma_f32_16x16x32_bf16 v[108:111], v[152:155], v[184:187], v[108:111]
	v_mfma_f32_16x16x32_bf16 v[96:99], v[144:147], v[218:221], v[96:99]
	v_mfma_f32_16x16x32_bf16 v[92:95], v[152:155], v[218:221], v[92:95]
	v_mfma_f32_16x16x32_bf16 v[80:83], v[144:147], v[226:229], v[80:83]
	v_mfma_f32_16x16x32_bf16 v[76:79], v[152:155], v[226:229], v[76:79]
	v_mfma_f32_16x16x32_bf16 v[128:131], v[148:151], v[180:183], v[128:131]
	v_mfma_f32_16x16x32_bf16 v[124:127], v[156:159], v[180:183], v[124:127]
	v_mfma_f32_16x16x32_bf16 v[112:115], v[148:151], v[214:217], v[112:115]
	v_mfma_f32_16x16x32_bf16 v[108:111], v[156:159], v[214:217], v[108:111]
	v_mfma_f32_16x16x32_bf16 v[96:99], v[148:151], v[222:225], v[96:99]
	v_mfma_f32_16x16x32_bf16 v[92:95], v[156:159], v[222:225], v[92:95]
	v_mfma_f32_16x16x32_bf16 v[80:83], v[148:151], v[230:233], v[80:83]
	v_mfma_f32_16x16x32_bf16 v[76:79], v[156:159], v[230:233], v[76:79]
	v_mfma_f32_16x16x32_bf16 v[120:123], v[160:163], v[176:179], v[120:123]
	v_mfma_f32_16x16x32_bf16 v[116:119], v[168:171], v[176:179], v[116:119]
	v_mfma_f32_16x16x32_bf16 v[104:107], v[160:163], v[184:187], v[104:107]
	v_mfma_f32_16x16x32_bf16 v[100:103], v[168:171], v[184:187], v[100:103]
	v_mfma_f32_16x16x32_bf16 v[88:91], v[160:163], v[218:221], v[88:91]
	v_mfma_f32_16x16x32_bf16 v[84:87], v[168:171], v[218:221], v[84:87]
	v_mfma_f32_16x16x32_bf16 v[72:75], v[160:163], v[226:229], v[72:75]
	v_mfma_f32_16x16x32_bf16 v[68:71], v[168:171], v[226:229], v[68:71]
	v_mfma_f32_16x16x32_bf16 v[120:123], v[164:167], v[180:183], v[120:123]
	v_mfma_f32_16x16x32_bf16 v[116:119], v[172:175], v[180:183], v[116:119]
	v_mfma_f32_16x16x32_bf16 v[104:107], v[164:167], v[214:217], v[104:107]
	v_mfma_f32_16x16x32_bf16 v[100:103], v[172:175], v[214:217], v[100:103]
	v_mfma_f32_16x16x32_bf16 v[88:91], v[164:167], v[222:225], v[88:91]
	v_mfma_f32_16x16x32_bf16 v[84:87], v[172:175], v[222:225], v[84:87]
	v_mfma_f32_16x16x32_bf16 v[72:75], v[164:167], v[230:233], v[72:75]
	v_mfma_f32_16x16x32_bf16 v[68:71], v[172:175], v[230:233], v[68:71]
	s_barrier
	s_add_i32 s18, s18, s46
	v_lshl_add_u64 v[188:189], s[22:23], 0, v[2:3]
	s_mov_b32 m0, s18
	ds_read_b128 v[176:179], v212 offset:16384
	ds_read_b128 v[180:183], v212 offset:17408
	ds_read_b128 v[184:187], v212 offset:18432
	ds_read_b128 v[214:217], v212 offset:19456
	ds_read_b128 v[218:221], v212 offset:20480
	ds_read_b128 v[222:225], v212 offset:21504
	ds_read_b128 v[226:229], v212 offset:22528
	ds_read_b128 v[230:233], v212 offset:23552
	global_load_lds_dwordx4 v[188:189], off
	s_add_i32 m0, s18, 0x2000
	s_add_u32 s18, s22, 0xb0000
	v_lshl_add_u64 v[196:197], s[22:23], 0, v[0:1]
	s_addc_u32 s19, s23, 0
	s_add_i32 s44, s62, s46
	global_load_lds_dwordx4 v[196:197], off
	v_lshl_add_u64 v[198:199], s[18:19], 0, v[2:3]
	s_mov_b32 m0, s44
	v_lshl_add_u64 v[200:201], s[24:25], 0, v[0:1]
	global_load_lds_dwordx4 v[198:199], off
	v_lshl_add_u64 v[198:199], s[18:19], 0, v[0:1]
	s_add_i32 m0, s44, 0x2000
	s_nop 0
	global_load_lds_dwordx4 v[198:199], off
	v_lshl_add_u64 v[198:199], s[24:25], 0, v[2:3]
	s_mov_b32 m0, s47
	s_nop 0
	global_load_lds_dwordx4 v[198:199], off
	s_mov_b32 m0, s48
	s_nop 0
	global_load_lds_dwordx4 v[200:201], off
	s_waitcnt vmcnt(8)
	s_waitcnt lgkmcnt(0)
	s_barrier
	s_waitcnt lgkmcnt(0)
	v_mfma_f32_16x16x32_bf16 v[64:67], v[144:147], v[176:179], v[64:67]
	v_mfma_f32_16x16x32_bf16 v[60:63], v[152:155], v[176:179], v[60:63]
	v_mfma_f32_16x16x32_bf16 v[48:51], v[144:147], v[184:187], v[48:51]
	v_mfma_f32_16x16x32_bf16 v[44:47], v[152:155], v[184:187], v[44:47]
	v_mfma_f32_16x16x32_bf16 v[32:35], v[144:147], v[218:221], v[32:35]
	v_mfma_f32_16x16x32_bf16 v[28:31], v[152:155], v[218:221], v[28:31]
	v_mfma_f32_16x16x32_bf16 v[16:19], v[144:147], v[226:229], v[16:19]
	v_mfma_f32_16x16x32_bf16 v[12:15], v[152:155], v[226:229], v[12:15]
	v_mfma_f32_16x16x32_bf16 v[64:67], v[148:151], v[180:183], v[64:67]
	v_mfma_f32_16x16x32_bf16 v[60:63], v[156:159], v[180:183], v[60:63]
	v_mfma_f32_16x16x32_bf16 v[48:51], v[148:151], v[214:217], v[48:51]
	v_mfma_f32_16x16x32_bf16 v[44:47], v[156:159], v[214:217], v[44:47]
	v_mfma_f32_16x16x32_bf16 v[32:35], v[148:151], v[222:225], v[32:35]
	v_mfma_f32_16x16x32_bf16 v[28:31], v[156:159], v[222:225], v[28:31]
	v_mfma_f32_16x16x32_bf16 v[16:19], v[148:151], v[230:233], v[16:19]
	v_mfma_f32_16x16x32_bf16 v[12:15], v[156:159], v[230:233], v[12:15]
	v_mfma_f32_16x16x32_bf16 v[56:59], v[160:163], v[176:179], v[56:59]
	v_mfma_f32_16x16x32_bf16 v[52:55], v[168:171], v[176:179], v[52:55]
	v_mfma_f32_16x16x32_bf16 v[40:43], v[160:163], v[184:187], v[40:43]
	v_mfma_f32_16x16x32_bf16 v[36:39], v[168:171], v[184:187], v[36:39]
	v_mfma_f32_16x16x32_bf16 v[24:27], v[160:163], v[218:221], v[24:27]
	v_mfma_f32_16x16x32_bf16 v[20:23], v[168:171], v[218:221], v[20:23]
	v_mfma_f32_16x16x32_bf16 v[8:11], v[160:163], v[226:229], v[8:11]
	v_mfma_f32_16x16x32_bf16 v[4:7], v[168:171], v[226:229], v[4:7]
	v_mfma_f32_16x16x32_bf16 v[56:59], v[164:167], v[180:183], v[56:59]
	v_mfma_f32_16x16x32_bf16 v[52:55], v[172:175], v[180:183], v[52:55]
	v_mfma_f32_16x16x32_bf16 v[40:43], v[164:167], v[214:217], v[40:43]
	v_mfma_f32_16x16x32_bf16 v[36:39], v[172:175], v[214:217], v[36:39]
	v_mfma_f32_16x16x32_bf16 v[24:27], v[164:167], v[222:225], v[24:27]
	v_mfma_f32_16x16x32_bf16 v[20:23], v[172:175], v[222:225], v[20:23]
	v_mfma_f32_16x16x32_bf16 v[8:11], v[164:167], v[230:233], v[8:11]
	v_mfma_f32_16x16x32_bf16 v[4:7], v[172:175], v[230:233], v[4:7]
	s_barrier
	s_add_i32 s44, 0, 0x18000
	s_add_i32 s45, 0, 0x1c000
	v_add_u32_e32 v156, s44, v210
	v_add_u32_e32 v172, s45, v210
	ds_read_b128 v[144:147], v156
	ds_read_b128 v[148:151], v156 offset:1024
	ds_read_b128 v[152:155], v156 offset:2048
	ds_read_b128 v[156:159], v156 offset:3072
	ds_read_b128 v[160:163], v172
	ds_read_b128 v[164:167], v172 offset:1024
	ds_read_b128 v[168:171], v172 offset:2048
	ds_read_b128 v[172:175], v172 offset:3072
	s_add_u32 s18, s24, 0xb0000
	s_addc_u32 s19, s25, 0
	s_mov_b32 m0, s49
	v_lshl_add_u64 v[234:235], s[18:19], 0, v[2:3]
	ds_read_b128 v[176:179], v212 offset:32768
	ds_read_b128 v[180:183], v212 offset:33792
	ds_read_b128 v[184:187], v212 offset:34816
	ds_read_b128 v[214:217], v212 offset:35840
	ds_read_b128 v[218:221], v212 offset:36864
	ds_read_b128 v[222:225], v212 offset:37888
	ds_read_b128 v[226:229], v212 offset:38912
	ds_read_b128 v[230:233], v212 offset:39936
	global_load_lds_dwordx4 v[234:235], off
	v_lshl_add_u64 v[234:235], s[18:19], 0, v[0:1]
	s_mov_b32 m0, s50
	s_nop 0
	global_load_lds_dwordx4 v[234:235], off
	s_waitcnt vmcnt(8)
	s_waitcnt lgkmcnt(0)
	s_barrier
	s_waitcnt lgkmcnt(0)
	v_mfma_f32_16x16x32_bf16 v[128:131], v[144:147], v[176:179], v[128:131]
	v_mfma_f32_16x16x32_bf16 v[124:127], v[152:155], v[176:179], v[124:127]
	v_mfma_f32_16x16x32_bf16 v[112:115], v[144:147], v[184:187], v[112:115]
	v_mfma_f32_16x16x32_bf16 v[108:111], v[152:155], v[184:187], v[108:111]
	v_mfma_f32_16x16x32_bf16 v[96:99], v[144:147], v[218:221], v[96:99]
	v_mfma_f32_16x16x32_bf16 v[92:95], v[152:155], v[218:221], v[92:95]
	v_mfma_f32_16x16x32_bf16 v[80:83], v[144:147], v[226:229], v[80:83]
	v_mfma_f32_16x16x32_bf16 v[76:79], v[152:155], v[226:229], v[76:79]
	v_mfma_f32_16x16x32_bf16 v[128:131], v[148:151], v[180:183], v[128:131]
	v_mfma_f32_16x16x32_bf16 v[124:127], v[156:159], v[180:183], v[124:127]
	v_mfma_f32_16x16x32_bf16 v[112:115], v[148:151], v[214:217], v[112:115]
	v_mfma_f32_16x16x32_bf16 v[108:111], v[156:159], v[214:217], v[108:111]
	v_mfma_f32_16x16x32_bf16 v[96:99], v[148:151], v[222:225], v[96:99]
	v_mfma_f32_16x16x32_bf16 v[92:95], v[156:159], v[222:225], v[92:95]
	v_mfma_f32_16x16x32_bf16 v[80:83], v[148:151], v[230:233], v[80:83]
	v_mfma_f32_16x16x32_bf16 v[76:79], v[156:159], v[230:233], v[76:79]
	v_mfma_f32_16x16x32_bf16 v[120:123], v[160:163], v[176:179], v[120:123]
	v_mfma_f32_16x16x32_bf16 v[116:119], v[168:171], v[176:179], v[116:119]
	v_mfma_f32_16x16x32_bf16 v[104:107], v[160:163], v[184:187], v[104:107]
	v_mfma_f32_16x16x32_bf16 v[100:103], v[168:171], v[184:187], v[100:103]
	v_mfma_f32_16x16x32_bf16 v[88:91], v[160:163], v[218:221], v[88:91]
	v_mfma_f32_16x16x32_bf16 v[84:87], v[168:171], v[218:221], v[84:87]
	v_mfma_f32_16x16x32_bf16 v[72:75], v[160:163], v[226:229], v[72:75]
	v_mfma_f32_16x16x32_bf16 v[68:71], v[168:171], v[226:229], v[68:71]
	v_mfma_f32_16x16x32_bf16 v[120:123], v[164:167], v[180:183], v[120:123]
	v_mfma_f32_16x16x32_bf16 v[116:119], v[172:175], v[180:183], v[116:119]
	v_mfma_f32_16x16x32_bf16 v[104:107], v[164:167], v[214:217], v[104:107]
	v_mfma_f32_16x16x32_bf16 v[100:103], v[172:175], v[214:217], v[100:103]
	v_mfma_f32_16x16x32_bf16 v[88:91], v[164:167], v[222:225], v[88:91]
	v_mfma_f32_16x16x32_bf16 v[84:87], v[172:175], v[222:225], v[84:87]
	v_mfma_f32_16x16x32_bf16 v[72:75], v[164:167], v[230:233], v[72:75]
	v_mfma_f32_16x16x32_bf16 v[68:71], v[172:175], v[230:233], v[68:71]
	s_barrier
	s_add_i32 s18, s44, s46
	v_lshl_add_u64 v[188:189], v[188:189], 0, s[92:93]
	s_mov_b32 m0, s18
	ds_read_b128 v[176:179], v212 offset:49152
	ds_read_b128 v[180:183], v212 offset:50176
	ds_read_b128 v[184:187], v212 offset:51200
	ds_read_b128 v[214:217], v212 offset:52224
	ds_read_b128 v[218:221], v212 offset:53248
	ds_read_b128 v[222:225], v212 offset:54272
	ds_read_b128 v[226:229], v212 offset:55296
	ds_read_b128 v[230:233], v212 offset:56320
	global_load_lds_dwordx4 v[188:189], off
	s_add_i32 m0, s18, 0x2000
	s_add_u32 s18, s22, 0xb0080
	v_lshl_add_u64 v[188:189], v[196:197], 0, s[92:93]
	s_addc_u32 s19, s23, 0
	s_add_i32 s22, s45, s46
	global_load_lds_dwordx4 v[188:189], off
	v_lshl_add_u64 v[188:189], s[18:19], 0, v[2:3]
	s_mov_b32 m0, s22
	s_nop 0
	global_load_lds_dwordx4 v[188:189], off
	v_lshl_add_u64 v[188:189], s[18:19], 0, v[0:1]
	s_add_i32 m0, s22, 0x2000
	s_nop 0
	global_load_lds_dwordx4 v[188:189], off
	v_lshl_add_u64 v[188:189], v[198:199], 0, s[92:93]
	s_mov_b32 m0, s52
	s_nop 0
	global_load_lds_dwordx4 v[188:189], off
	v_lshl_add_u64 v[188:189], v[200:201], 0, s[92:93]
	s_mov_b32 m0, s53
	s_nop 0
	global_load_lds_dwordx4 v[188:189], off
	s_waitcnt vmcnt(8)
	s_waitcnt lgkmcnt(0)
	s_barrier
	s_waitcnt lgkmcnt(0)
	v_mfma_f32_16x16x32_bf16 v[64:67], v[144:147], v[176:179], v[64:67]
	v_mfma_f32_16x16x32_bf16 v[60:63], v[152:155], v[176:179], v[60:63]
	v_mfma_f32_16x16x32_bf16 v[48:51], v[144:147], v[184:187], v[48:51]
	v_mfma_f32_16x16x32_bf16 v[44:47], v[152:155], v[184:187], v[44:47]
	v_mfma_f32_16x16x32_bf16 v[32:35], v[144:147], v[218:221], v[32:35]
	v_mfma_f32_16x16x32_bf16 v[28:31], v[152:155], v[218:221], v[28:31]
	v_mfma_f32_16x16x32_bf16 v[16:19], v[144:147], v[226:229], v[16:19]
	v_mfma_f32_16x16x32_bf16 v[12:15], v[152:155], v[226:229], v[12:15]
	v_mfma_f32_16x16x32_bf16 v[64:67], v[148:151], v[180:183], v[64:67]
	v_mfma_f32_16x16x32_bf16 v[60:63], v[156:159], v[180:183], v[60:63]
	v_mfma_f32_16x16x32_bf16 v[48:51], v[148:151], v[214:217], v[48:51]
	v_mfma_f32_16x16x32_bf16 v[44:47], v[156:159], v[214:217], v[44:47]
	v_mfma_f32_16x16x32_bf16 v[32:35], v[148:151], v[222:225], v[32:35]
	v_mfma_f32_16x16x32_bf16 v[28:31], v[156:159], v[222:225], v[28:31]
	v_mfma_f32_16x16x32_bf16 v[16:19], v[148:151], v[230:233], v[16:19]
	v_mfma_f32_16x16x32_bf16 v[12:15], v[156:159], v[230:233], v[12:15]
	v_mfma_f32_16x16x32_bf16 v[56:59], v[160:163], v[176:179], v[56:59]
	v_mfma_f32_16x16x32_bf16 v[52:55], v[168:171], v[176:179], v[52:55]
	v_mfma_f32_16x16x32_bf16 v[40:43], v[160:163], v[184:187], v[40:43]
	v_mfma_f32_16x16x32_bf16 v[36:39], v[168:171], v[184:187], v[36:39]
	v_mfma_f32_16x16x32_bf16 v[24:27], v[160:163], v[218:221], v[24:27]
	v_mfma_f32_16x16x32_bf16 v[20:23], v[168:171], v[218:221], v[20:23]
	v_mfma_f32_16x16x32_bf16 v[8:11], v[160:163], v[226:229], v[8:11]
	v_mfma_f32_16x16x32_bf16 v[4:7], v[168:171], v[226:229], v[4:7]
	v_mfma_f32_16x16x32_bf16 v[56:59], v[164:167], v[180:183], v[56:59]
	v_mfma_f32_16x16x32_bf16 v[52:55], v[172:175], v[180:183], v[52:55]
	v_mfma_f32_16x16x32_bf16 v[40:43], v[164:167], v[214:217], v[40:43]
	v_mfma_f32_16x16x32_bf16 v[36:39], v[172:175], v[214:217], v[36:39]
	v_mfma_f32_16x16x32_bf16 v[24:27], v[164:167], v[222:225], v[24:27]
	v_mfma_f32_16x16x32_bf16 v[20:23], v[172:175], v[222:225], v[20:23]
	v_mfma_f32_16x16x32_bf16 v[8:11], v[164:167], v[230:233], v[8:11]
	v_mfma_f32_16x16x32_bf16 v[4:7], v[172:175], v[230:233], v[4:7]
	s_barrier
	s_add_i32 s15, s15, 2
	s_add_u32 s13, s13, 0x100
	s_addc_u32 s14, s14, 0
	s_cmp_gt_u32 s15, 41
	s_mov_b64 s[44:45], s[42:43]
	s_cbranch_scc0 .LBB0_811
	s_setprio 0
	s_and_b64 vcc, exec, s[4:5]
	s_cbranch_vccz .LBB0_814
	s_barrier

.LBB0_927:
	s_ashr_i32 s7, s6, 31
	s_lshl_b64 s[10:11], s[6:7], 19
	s_add_u32 s10, s20, s10
	s_addc_u32 s11, s21, s11
	s_and_b64 s[14:15], s[38:39], exec
	s_cselect_b32 s7, s11, s23
	s_cselect_b32 s13, s10, s22
	s_ashr_i32 s5, s4, 31
	s_lshl_b64 s[14:15], s[4:5], 19
	s_add_u32 s14, s26, s14
	s_addc_u32 s15, s27, s15
	s_and_b64 s[18:19], s[38:39], exec
	s_cselect_b32 s5, s15, s43
	s_cselect_b32 s17, s14, s42
	s_add_u32 s40, s22, 0x40080
	s_addc_u32 s41, s23, 0
	s_add_u32 s42, s42, 0x100
	v_mov_b32_e32 v4, 0
	s_addc_u32 s43, s43, 0
	s_mov_b32 s51, -2
	v_mov_b32_e32 v5, v4
	v_mov_b32_e32 v6, v4
	v_mov_b32_e32 v7, v4
	v_mov_b32_e32 v8, v4
	v_mov_b32_e32 v9, v4
	v_mov_b32_e32 v10, v4
	v_mov_b32_e32 v11, v4
	v_mov_b32_e32 v16, v4
	v_mov_b32_e32 v17, v4
	v_mov_b32_e32 v18, v4
	v_mov_b32_e32 v19, v4
	v_mov_b32_e32 v24, v4
	v_mov_b32_e32 v25, v4
	v_mov_b32_e32 v26, v4
	v_mov_b32_e32 v27, v4
	v_mov_b32_e32 v32, v4
	v_mov_b32_e32 v33, v4
	v_mov_b32_e32 v34, v4
	v_mov_b32_e32 v35, v4
	v_mov_b32_e32 v40, v4
	v_mov_b32_e32 v41, v4
	v_mov_b32_e32 v42, v4
	v_mov_b32_e32 v43, v4
	v_mov_b32_e32 v48, v4
	v_mov_b32_e32 v49, v4
	v_mov_b32_e32 v50, v4
	v_mov_b32_e32 v51, v4
	v_mov_b32_e32 v56, v4
	v_mov_b32_e32 v57, v4
	v_mov_b32_e32 v58, v4
	v_mov_b32_e32 v59, v4
	v_mov_b32_e32 v12, v4
	v_mov_b32_e32 v13, v4
	v_mov_b32_e32 v14, v4
	v_mov_b32_e32 v15, v4
	v_mov_b32_e32 v20, v4
	v_mov_b32_e32 v21, v4
	v_mov_b32_e32 v22, v4
	v_mov_b32_e32 v23, v4
	v_mov_b32_e32 v28, v4
	v_mov_b32_e32 v29, v4
	v_mov_b32_e32 v30, v4
	v_mov_b32_e32 v31, v4
	v_mov_b32_e32 v36, v4
	v_mov_b32_e32 v37, v4
	v_mov_b32_e32 v38, v4
	v_mov_b32_e32 v39, v4
	v_mov_b32_e32 v44, v4
	v_mov_b32_e32 v45, v4
	v_mov_b32_e32 v46, v4
	v_mov_b32_e32 v47, v4
	v_mov_b32_e32 v52, v4
	v_mov_b32_e32 v53, v4
	v_mov_b32_e32 v54, v4
	v_mov_b32_e32 v55, v4
	v_mov_b32_e32 v60, v4
	v_mov_b32_e32 v61, v4
	v_mov_b32_e32 v62, v4
	v_mov_b32_e32 v63, v4
	v_mov_b32_e32 v64, v4
	v_mov_b32_e32 v65, v4
	v_mov_b32_e32 v66, v4
	v_mov_b32_e32 v67, v4
	v_mov_b32_e32 v68, v4
	v_mov_b32_e32 v69, v4
	v_mov_b32_e32 v70, v4
	v_mov_b32_e32 v71, v4
	v_mov_b32_e32 v72, v4
	v_mov_b32_e32 v73, v4
	v_mov_b32_e32 v74, v4
	v_mov_b32_e32 v75, v4
	v_mov_b32_e32 v80, v4
	v_mov_b32_e32 v81, v4
	v_mov_b32_e32 v82, v4
	v_mov_b32_e32 v83, v4
	v_mov_b32_e32 v88, v4
	v_mov_b32_e32 v89, v4
	v_mov_b32_e32 v90, v4
	v_mov_b32_e32 v91, v4
	v_mov_b32_e32 v96, v4
	v_mov_b32_e32 v97, v4
	v_mov_b32_e32 v98, v4
	v_mov_b32_e32 v99, v4
	v_mov_b32_e32 v104, v4
	v_mov_b32_e32 v105, v4
	v_mov_b32_e32 v106, v4
	v_mov_b32_e32 v107, v4
	v_mov_b32_e32 v112, v4
	v_mov_b32_e32 v113, v4
	v_mov_b32_e32 v114, v4
	v_mov_b32_e32 v115, v4
	v_mov_b32_e32 v120, v4
	v_mov_b32_e32 v121, v4
	v_mov_b32_e32 v122, v4
	v_mov_b32_e32 v123, v4
	v_mov_b32_e32 v76, v4
	v_mov_b32_e32 v77, v4
	v_mov_b32_e32 v78, v4
	v_mov_b32_e32 v79, v4
	v_mov_b32_e32 v84, v4
	v_mov_b32_e32 v85, v4
	v_mov_b32_e32 v86, v4
	v_mov_b32_e32 v87, v4
	v_mov_b32_e32 v92, v4
	v_mov_b32_e32 v93, v4
	v_mov_b32_e32 v94, v4
	v_mov_b32_e32 v95, v4
	v_mov_b32_e32 v100, v4
	v_mov_b32_e32 v101, v4
	v_mov_b32_e32 v102, v4
	v_mov_b32_e32 v103, v4
	v_mov_b32_e32 v108, v4
	v_mov_b32_e32 v109, v4
	v_mov_b32_e32 v110, v4
	v_mov_b32_e32 v111, v4
	v_mov_b32_e32 v116, v4
	v_mov_b32_e32 v117, v4
	v_mov_b32_e32 v118, v4
	v_mov_b32_e32 v119, v4
	v_mov_b32_e32 v124, v4
	v_mov_b32_e32 v125, v4
	v_mov_b32_e32 v126, v4
	v_mov_b32_e32 v127, v4
	v_mov_b32_e32 v128, v4
	v_mov_b32_e32 v129, v4
	v_mov_b32_e32 v130, v4
	v_mov_b32_e32 v131, v4
	s_waitcnt vmcnt(0)
	v_readfirstlane_b32 s100, v207
	s_bitcmp1_b32 s100, 8
	s_cbranch_scc0 .Lprio_skip_928
	s_setprio 1
.Lprio_skip_928:
.LBB0_928:
	s_add_u32 s18, s40, 0xfffc0080
	s_addc_u32 s19, s41, -1
	s_add_i32 s52, 0, 0x10000
	s_cmp_eq_u32 s51, 12
	s_cselect_b32 s25, s7, s19
	s_cselect_b32 s24, s13, s18
	s_cselect_b32 s23, s5, s43
	s_cselect_b32 s22, s17, s42
	s_add_i32 s53, 0, 0x14000
	v_add_u32_e32 v166, s52, v152
	v_add_u32_e32 v182, s53, v152
	ds_read_b128 v[148:151], v166
	ds_read_b128 v[158:161], v166 offset:1024
	ds_read_b128 v[162:165], v166 offset:2048
	ds_read_b128 v[166:169], v166 offset:3072
	ds_read_b128 v[170:173], v182
	ds_read_b128 v[174:177], v182 offset:1024
	ds_read_b128 v[178:181], v182 offset:2048
	ds_read_b128 v[182:185], v182 offset:3072
	v_lshl_add_u64 v[236:237], s[40:41], 0, v[144:145]
	s_add_i32 m0, s29, 0xc000
	ds_read_b128 v[186:189], v157
	ds_read_b128 v[208:211], v157 offset:1024
	ds_read_b128 v[212:215], v157 offset:2048
	ds_read_b128 v[216:219], v157 offset:3072
	ds_read_b128 v[220:223], v157 offset:4096
	ds_read_b128 v[224:227], v157 offset:5120
	ds_read_b128 v[228:231], v157 offset:6144
	ds_read_b128 v[232:235], v157 offset:7168
	global_load_lds_dwordx4 v[236:237], off
	v_lshl_add_u64 v[236:237], s[40:41], 0, v[146:147]
	s_add_i32 m0, s29, 0xe000
	s_nop 0
	global_load_lds_dwordx4 v[236:237], off
	s_waitcnt vmcnt(8)
	s_waitcnt lgkmcnt(0)
	s_barrier
	s_waitcnt lgkmcnt(0)
	v_mfma_f32_16x16x32_bf16 v[128:131], v[148:151], v[186:189], v[128:131]
	v_mfma_f32_16x16x32_bf16 v[124:127], v[162:165], v[186:189], v[124:127]
	v_mfma_f32_16x16x32_bf16 v[116:119], v[148:151], v[212:215], v[116:119]
	v_mfma_f32_16x16x32_bf16 v[108:111], v[162:165], v[212:215], v[108:111]
	v_mfma_f32_16x16x32_bf16 v[100:103], v[148:151], v[220:223], v[100:103]
	v_mfma_f32_16x16x32_bf16 v[92:95], v[162:165], v[220:223], v[92:95]
	v_mfma_f32_16x16x32_bf16 v[84:87], v[148:151], v[228:231], v[84:87]
	v_mfma_f32_16x16x32_bf16 v[76:79], v[162:165], v[228:231], v[76:79]
	v_mfma_f32_16x16x32_bf16 v[128:131], v[158:161], v[208:211], v[128:131]
	v_mfma_f32_16x16x32_bf16 v[124:127], v[166:169], v[208:211], v[124:127]
	v_mfma_f32_16x16x32_bf16 v[116:119], v[158:161], v[216:219], v[116:119]
	v_mfma_f32_16x16x32_bf16 v[108:111], v[166:169], v[216:219], v[108:111]
	v_mfma_f32_16x16x32_bf16 v[100:103], v[158:161], v[224:227], v[100:103]
	v_mfma_f32_16x16x32_bf16 v[92:95], v[166:169], v[224:227], v[92:95]
	v_mfma_f32_16x16x32_bf16 v[84:87], v[158:161], v[232:235], v[84:87]
	v_mfma_f32_16x16x32_bf16 v[76:79], v[166:169], v[232:235], v[76:79]
	v_mfma_f32_16x16x32_bf16 v[120:123], v[170:173], v[186:189], v[120:123]
	v_mfma_f32_16x16x32_bf16 v[112:115], v[178:181], v[186:189], v[112:115]
	v_mfma_f32_16x16x32_bf16 v[104:107], v[170:173], v[212:215], v[104:107]
	v_mfma_f32_16x16x32_bf16 v[96:99], v[178:181], v[212:215], v[96:99]
	v_mfma_f32_16x16x32_bf16 v[88:91], v[170:173], v[220:223], v[88:91]
	v_mfma_f32_16x16x32_bf16 v[80:83], v[178:181], v[220:223], v[80:83]
	v_mfma_f32_16x16x32_bf16 v[72:75], v[170:173], v[228:231], v[72:75]
	v_mfma_f32_16x16x32_bf16 v[68:71], v[178:181], v[228:231], v[68:71]
	v_mfma_f32_16x16x32_bf16 v[120:123], v[174:177], v[208:211], v[120:123]
	v_mfma_f32_16x16x32_bf16 v[112:115], v[182:185], v[208:211], v[112:115]
	v_mfma_f32_16x16x32_bf16 v[104:107], v[174:177], v[216:219], v[104:107]
	v_mfma_f32_16x16x32_bf16 v[96:99], v[182:185], v[216:219], v[96:99]
	v_mfma_f32_16x16x32_bf16 v[88:91], v[174:177], v[224:227], v[88:91]
	v_mfma_f32_16x16x32_bf16 v[80:83], v[182:185], v[224:227], v[80:83]
	v_mfma_f32_16x16x32_bf16 v[72:75], v[174:177], v[232:235], v[72:75]
	v_mfma_f32_16x16x32_bf16 v[68:71], v[182:185], v[232:235], v[68:71]
	s_barrier
	s_add_i32 s18, s52, s28
	v_lshl_add_u64 v[236:237], s[22:23], 0, v[2:3]
	s_mov_b32 m0, s18
	ds_read_b128 v[186:189], v157 offset:16384
	ds_read_b128 v[208:211], v157 offset:17408
	ds_read_b128 v[212:215], v157 offset:18432
	ds_read_b128 v[216:219], v157 offset:19456
	ds_read_b128 v[220:223], v157 offset:20480
	ds_read_b128 v[224:227], v157 offset:21504
	ds_read_b128 v[228:231], v157 offset:22528
	ds_read_b128 v[232:235], v157 offset:23552
	global_load_lds_dwordx4 v[236:237], off
	s_add_i32 m0, s18, 0x2000
	s_add_u32 s18, s22, 0x10000
	v_lshl_add_u64 v[238:239], s[22:23], 0, v[142:143]
	s_addc_u32 s19, s23, 0
	s_add_i32 s52, s53, s28
	global_load_lds_dwordx4 v[238:239], off
	v_lshl_add_u64 v[240:241], s[18:19], 0, v[2:3]
	s_mov_b32 m0, s52
	v_lshl_add_u64 v[242:243], s[24:25], 0, v[140:141]
	global_load_lds_dwordx4 v[240:241], off
	v_lshl_add_u64 v[240:241], s[18:19], 0, v[142:143]
	s_add_i32 m0, s52, 0x2000
	s_nop 0
	global_load_lds_dwordx4 v[240:241], off
	v_lshl_add_u64 v[240:241], s[24:25], 0, v[0:1]
	s_mov_b32 m0, s29
	s_nop 0
	global_load_lds_dwordx4 v[240:241], off
	s_mov_b32 m0, s44
	s_nop 0
	global_load_lds_dwordx4 v[242:243], off
	s_waitcnt vmcnt(8)
	s_waitcnt lgkmcnt(0)
	s_barrier
	s_waitcnt lgkmcnt(0)
	v_mfma_f32_16x16x32_bf16 v[64:67], v[148:151], v[186:189], v[64:67]
	v_mfma_f32_16x16x32_bf16 v[60:63], v[162:165], v[186:189], v[60:63]
	v_mfma_f32_16x16x32_bf16 v[52:55], v[148:151], v[212:215], v[52:55]
	v_mfma_f32_16x16x32_bf16 v[44:47], v[162:165], v[212:215], v[44:47]
	v_mfma_f32_16x16x32_bf16 v[36:39], v[148:151], v[220:223], v[36:39]
	v_mfma_f32_16x16x32_bf16 v[28:31], v[162:165], v[220:223], v[28:31]
	v_mfma_f32_16x16x32_bf16 v[20:23], v[148:151], v[228:231], v[20:23]
	v_mfma_f32_16x16x32_bf16 v[12:15], v[162:165], v[228:231], v[12:15]
	v_mfma_f32_16x16x32_bf16 v[64:67], v[158:161], v[208:211], v[64:67]
	v_mfma_f32_16x16x32_bf16 v[60:63], v[166:169], v[208:211], v[60:63]
	v_mfma_f32_16x16x32_bf16 v[52:55], v[158:161], v[216:219], v[52:55]
	v_mfma_f32_16x16x32_bf16 v[44:47], v[166:169], v[216:219], v[44:47]
	v_mfma_f32_16x16x32_bf16 v[36:39], v[158:161], v[224:227], v[36:39]
	v_mfma_f32_16x16x32_bf16 v[28:31], v[166:169], v[224:227], v[28:31]
	v_mfma_f32_16x16x32_bf16 v[20:23], v[158:161], v[232:235], v[20:23]
	v_mfma_f32_16x16x32_bf16 v[12:15], v[166:169], v[232:235], v[12:15]
	v_mfma_f32_16x16x32_bf16 v[56:59], v[170:173], v[186:189], v[56:59]
	v_mfma_f32_16x16x32_bf16 v[48:51], v[178:181], v[186:189], v[48:51]
	v_mfma_f32_16x16x32_bf16 v[40:43], v[170:173], v[212:215], v[40:43]
	v_mfma_f32_16x16x32_bf16 v[32:35], v[178:181], v[212:215], v[32:35]
	v_mfma_f32_16x16x32_bf16 v[24:27], v[170:173], v[220:223], v[24:27]
	v_mfma_f32_16x16x32_bf16 v[16:19], v[178:181], v[220:223], v[16:19]
	v_mfma_f32_16x16x32_bf16 v[8:11], v[170:173], v[228:231], v[8:11]
	v_mfma_f32_16x16x32_bf16 v[4:7], v[178:181], v[228:231], v[4:7]
	v_mfma_f32_16x16x32_bf16 v[56:59], v[174:177], v[208:211], v[56:59]
	v_mfma_f32_16x16x32_bf16 v[48:51], v[182:185], v[208:211], v[48:51]
	v_mfma_f32_16x16x32_bf16 v[40:43], v[174:177], v[216:219], v[40:43]
	v_mfma_f32_16x16x32_bf16 v[32:35], v[182:185], v[216:219], v[32:35]
	v_mfma_f32_16x16x32_bf16 v[24:27], v[174:177], v[224:227], v[24:27]
	v_mfma_f32_16x16x32_bf16 v[16:19], v[182:185], v[224:227], v[16:19]
	v_mfma_f32_16x16x32_bf16 v[8:11], v[174:177], v[232:235], v[8:11]
	v_mfma_f32_16x16x32_bf16 v[4:7], v[182:185], v[232:235], v[4:7]
	s_barrier
	s_add_i32 s52, 0, 0x18000
	s_add_i32 s53, 0, 0x1c000
	v_add_u32_e32 v166, s52, v152
	v_add_u32_e32 v182, s53, v152
	ds_read_b128 v[148:151], v166
	ds_read_b128 v[158:161], v166 offset:1024
	ds_read_b128 v[162:165], v166 offset:2048
	ds_read_b128 v[166:169], v166 offset:3072
	ds_read_b128 v[170:173], v182
	ds_read_b128 v[174:177], v182 offset:1024
	ds_read_b128 v[178:181], v182 offset:2048
	ds_read_b128 v[182:185], v182 offset:3072
	s_add_u32 s18, s24, 0x40000
	s_addc_u32 s19, s25, 0
	s_mov_b32 m0, s45
	v_lshl_add_u64 v[244:245], s[18:19], 0, v[0:1]
	ds_read_b128 v[186:189], v157 offset:32768
	ds_read_b128 v[208:211], v157 offset:33792
	ds_read_b128 v[212:215], v157 offset:34816
	ds_read_b128 v[216:219], v157 offset:35840
	ds_read_b128 v[220:223], v157 offset:36864
	ds_read_b128 v[224:227], v157 offset:37888
	ds_read_b128 v[228:231], v157 offset:38912
	ds_read_b128 v[232:235], v157 offset:39936
	global_load_lds_dwordx4 v[244:245], off
	v_lshl_add_u64 v[244:245], s[18:19], 0, v[140:141]
	s_mov_b32 m0, s46
	s_nop 0
	global_load_lds_dwordx4 v[244:245], off
	s_waitcnt vmcnt(8)
	s_waitcnt lgkmcnt(0)
	s_barrier
	s_waitcnt lgkmcnt(0)
	v_mfma_f32_16x16x32_bf16 v[128:131], v[148:151], v[186:189], v[128:131]
	v_mfma_f32_16x16x32_bf16 v[124:127], v[162:165], v[186:189], v[124:127]
	v_mfma_f32_16x16x32_bf16 v[116:119], v[148:151], v[212:215], v[116:119]
	v_mfma_f32_16x16x32_bf16 v[108:111], v[162:165], v[212:215], v[108:111]
	v_mfma_f32_16x16x32_bf16 v[100:103], v[148:151], v[220:223], v[100:103]
	v_mfma_f32_16x16x32_bf16 v[92:95], v[162:165], v[220:223], v[92:95]
	v_mfma_f32_16x16x32_bf16 v[84:87], v[148:151], v[228:231], v[84:87]
	v_mfma_f32_16x16x32_bf16 v[76:79], v[162:165], v[228:231], v[76:79]
	v_mfma_f32_16x16x32_bf16 v[128:131], v[158:161], v[208:211], v[128:131]
	v_mfma_f32_16x16x32_bf16 v[124:127], v[166:169], v[208:211], v[124:127]
	v_mfma_f32_16x16x32_bf16 v[116:119], v[158:161], v[216:219], v[116:119]
	v_mfma_f32_16x16x32_bf16 v[108:111], v[166:169], v[216:219], v[108:111]
	v_mfma_f32_16x16x32_bf16 v[100:103], v[158:161], v[224:227], v[100:103]
	v_mfma_f32_16x16x32_bf16 v[92:95], v[166:169], v[224:227], v[92:95]
	v_mfma_f32_16x16x32_bf16 v[84:87], v[158:161], v[232:235], v[84:87]
	v_mfma_f32_16x16x32_bf16 v[76:79], v[166:169], v[232:235], v[76:79]
	v_mfma_f32_16x16x32_bf16 v[120:123], v[170:173], v[186:189], v[120:123]
	v_mfma_f32_16x16x32_bf16 v[112:115], v[178:181], v[186:189], v[112:115]
	v_mfma_f32_16x16x32_bf16 v[104:107], v[170:173], v[212:215], v[104:107]
	v_mfma_f32_16x16x32_bf16 v[96:99], v[178:181], v[212:215], v[96:99]
	v_mfma_f32_16x16x32_bf16 v[88:91], v[170:173], v[220:223], v[88:91]
	v_mfma_f32_16x16x32_bf16 v[80:83], v[178:181], v[220:223], v[80:83]
	v_mfma_f32_16x16x32_bf16 v[72:75], v[170:173], v[228:231], v[72:75]
	v_mfma_f32_16x16x32_bf16 v[68:71], v[178:181], v[228:231], v[68:71]
	v_mfma_f32_16x16x32_bf16 v[120:123], v[174:177], v[208:211], v[120:123]
	v_mfma_f32_16x16x32_bf16 v[112:115], v[182:185], v[208:211], v[112:115]
	v_mfma_f32_16x16x32_bf16 v[104:107], v[174:177], v[216:219], v[104:107]
	v_mfma_f32_16x16x32_bf16 v[96:99], v[182:185], v[216:219], v[96:99]
	v_mfma_f32_16x16x32_bf16 v[88:91], v[174:177], v[224:227], v[88:91]
	v_mfma_f32_16x16x32_bf16 v[80:83], v[182:185], v[224:227], v[80:83]
	v_mfma_f32_16x16x32_bf16 v[72:75], v[174:177], v[232:235], v[72:75]
	v_mfma_f32_16x16x32_bf16 v[68:71], v[182:185], v[232:235], v[68:71]
	s_barrier
	s_add_i32 s18, s52, s28
	v_lshl_add_u64 v[236:237], v[236:237], 0, s[92:93]
	s_mov_b32 m0, s18
	ds_read_b128 v[186:189], v157 offset:49152
	ds_read_b128 v[208:211], v157 offset:50176
	ds_read_b128 v[212:215], v157 offset:51200
	ds_read_b128 v[216:219], v157 offset:52224
	ds_read_b128 v[220:223], v157 offset:53248
	ds_read_b128 v[224:227], v157 offset:54272
	ds_read_b128 v[228:231], v157 offset:55296
	ds_read_b128 v[232:235], v157 offset:56320
	global_load_lds_dwordx4 v[236:237], off
	s_add_i32 m0, s18, 0x2000
	s_add_u32 s18, s22, 0x10080
	v_lshl_add_u64 v[236:237], v[238:239], 0, s[92:93]
	s_addc_u32 s19, s23, 0
	s_add_i32 s22, s53, s28
	global_load_lds_dwordx4 v[236:237], off
	v_lshl_add_u64 v[236:237], s[18:19], 0, v[2:3]
	s_mov_b32 m0, s22
	s_nop 0
	global_load_lds_dwordx4 v[236:237], off
	v_lshl_add_u64 v[236:237], s[18:19], 0, v[142:143]
	s_add_i32 m0, s22, 0x2000
	s_nop 0
	global_load_lds_dwordx4 v[236:237], off
	v_lshl_add_u64 v[236:237], v[240:241], 0, s[92:93]
	s_mov_b32 m0, s47
	s_nop 0
	global_load_lds_dwordx4 v[236:237], off
	v_lshl_add_u64 v[236:237], v[242:243], 0, s[92:93]
	s_mov_b32 m0, s48
	s_nop 0
	global_load_lds_dwordx4 v[236:237], off
	s_waitcnt vmcnt(8)
	s_waitcnt lgkmcnt(0)
	s_barrier
	s_waitcnt lgkmcnt(0)
	v_mfma_f32_16x16x32_bf16 v[64:67], v[148:151], v[186:189], v[64:67]
	v_mfma_f32_16x16x32_bf16 v[60:63], v[162:165], v[186:189], v[60:63]
	v_mfma_f32_16x16x32_bf16 v[52:55], v[148:151], v[212:215], v[52:55]
	v_mfma_f32_16x16x32_bf16 v[44:47], v[162:165], v[212:215], v[44:47]
	v_mfma_f32_16x16x32_bf16 v[36:39], v[148:151], v[220:223], v[36:39]
	v_mfma_f32_16x16x32_bf16 v[28:31], v[162:165], v[220:223], v[28:31]
	v_mfma_f32_16x16x32_bf16 v[20:23], v[148:151], v[228:231], v[20:23]
	v_mfma_f32_16x16x32_bf16 v[12:15], v[162:165], v[228:231], v[12:15]
	v_mfma_f32_16x16x32_bf16 v[64:67], v[158:161], v[208:211], v[64:67]
	v_mfma_f32_16x16x32_bf16 v[60:63], v[166:169], v[208:211], v[60:63]
	v_mfma_f32_16x16x32_bf16 v[52:55], v[158:161], v[216:219], v[52:55]
	v_mfma_f32_16x16x32_bf16 v[44:47], v[166:169], v[216:219], v[44:47]
	v_mfma_f32_16x16x32_bf16 v[36:39], v[158:161], v[224:227], v[36:39]
	v_mfma_f32_16x16x32_bf16 v[28:31], v[166:169], v[224:227], v[28:31]
	v_mfma_f32_16x16x32_bf16 v[20:23], v[158:161], v[232:235], v[20:23]
	v_mfma_f32_16x16x32_bf16 v[12:15], v[166:169], v[232:235], v[12:15]
	v_mfma_f32_16x16x32_bf16 v[56:59], v[170:173], v[186:189], v[56:59]
	v_mfma_f32_16x16x32_bf16 v[48:51], v[178:181], v[186:189], v[48:51]
	v_mfma_f32_16x16x32_bf16 v[40:43], v[170:173], v[212:215], v[40:43]
	v_mfma_f32_16x16x32_bf16 v[32:35], v[178:181], v[212:215], v[32:35]
	v_mfma_f32_16x16x32_bf16 v[24:27], v[170:173], v[220:223], v[24:27]
	v_mfma_f32_16x16x32_bf16 v[16:19], v[178:181], v[220:223], v[16:19]
	v_mfma_f32_16x16x32_bf16 v[8:11], v[170:173], v[228:231], v[8:11]
	v_mfma_f32_16x16x32_bf16 v[4:7], v[178:181], v[228:231], v[4:7]
	v_mfma_f32_16x16x32_bf16 v[56:59], v[174:177], v[208:211], v[56:59]
	v_mfma_f32_16x16x32_bf16 v[48:51], v[182:185], v[208:211], v[48:51]
	v_mfma_f32_16x16x32_bf16 v[40:43], v[174:177], v[216:219], v[40:43]
	v_mfma_f32_16x16x32_bf16 v[32:35], v[182:185], v[216:219], v[32:35]
	v_mfma_f32_16x16x32_bf16 v[24:27], v[174:177], v[224:227], v[24:27]
	v_mfma_f32_16x16x32_bf16 v[16:19], v[182:185], v[224:227], v[16:19]
	v_mfma_f32_16x16x32_bf16 v[8:11], v[174:177], v[232:235], v[8:11]
	v_mfma_f32_16x16x32_bf16 v[4:7], v[182:185], v[232:235], v[4:7]
	s_barrier
	s_add_i32 s51, s51, 2
	s_add_u32 s40, s40, 0x100
	s_addc_u32 s41, s41, 0
	s_add_u32 s42, s42, 0x100
	s_addc_u32 s43, s43, 0
	s_cmp_gt_u32 s51, 13
	s_cbranch_scc0 .LBB0_928
	s_setprio 0
	s_lshl_b32 s5, s16, 8
	s_and_b64 vcc, exec, s[2:3]
	s_cbranch_vccz .LBB0_931
	v_or_b32_e32 v148, s5, v154
	v_ashrrev_i32_e32 v149, 31, v148
	v_lshlrev_b64 v[148:149], 6, v[148:149]
	v_lshl_add_u64 v[166:167], s[74:75], 0, v[148:149]
	global_load_dwordx4 v[148:151], v[166:167], off
	global_load_dwordx4 v[158:161], v[166:167], off offset:32
	global_load_dwordx4 v[162:165], v[166:167], off offset:16
	s_nop 0
	global_load_dwordx4 v[166:169], v[166:167], off offset:48
	s_barrier
